# speedup vs baseline: 1.0020x; 1.0020x over previous
.LBB0_161:
	s_cmpk_lg_i32 s46, 0xf00
	s_cselect_b64 s[22:23], -1, 0
	s_cmpk_eq_i32 s46, 0xf00
	s_cbranch_scc1 .LBB0_163
	v_lshl_add_u64 v[0:1], v[118:119], 0, s[68:69]
	v_lshl_add_u64 v[120:121], v[104:105], 0, s[86:87]
	global_load_dwordx4 v[16:19], v[120:121], off offset:-128
	global_load_dwordx4 v[150:153], v[120:121], off offset:-96
	global_load_dwordx4 v[154:157], v[120:121], off offset:-64
	global_load_dwordx4 v[158:161], v[120:121], off offset:-32
	global_load_dwordx4 v[186:189], v[120:121], off
	global_load_dwordx4 v[190:193], v[120:121], off offset:32
	global_load_dwordx4 v[194:197], v[120:121], off offset:64
	global_load_dwordx4 v[198:201], v[120:121], off offset:96
	global_load_dwordx4 v[92:95], v[0:1], off
	global_load_dwordx4 v[88:91], v[0:1], off offset:32
	global_load_dwordx4 v[84:87], v[0:1], off offset:64
	global_load_dwordx4 v[80:83], v[0:1], off offset:96
	v_lshl_add_u64 v[0:1], v[102:103], 0, s[46:47]
	v_add_co_u32_e32 v2, vcc, 0x3c01000, v0
	v_lshl_add_u64 v[4:5], v[100:101], 0, s[46:47]
	s_nop 0
	v_addc_co_u32_e32 v3, vcc, 0, v1, vcc
	v_add_co_u32_e32 v6, vcc, 0x3c01000, v4
	v_lshl_add_u64 v[8:9], v[96:97], 0, s[46:47]
	s_nop 0
	v_addc_co_u32_e32 v7, vcc, 0, v5, vcc
	global_load_dwordx4 v[32:35], v[2:3], off offset:256 nt
	global_load_dwordx4 v[36:39], v[6:7], off offset:256 nt
	v_lshl_add_u64 v[2:3], v[98:99], 0, s[46:47]
	v_add_co_u32_e32 v6, vcc, 0x3c01000, v2
	s_nop 1
	v_addc_co_u32_e32 v7, vcc, 0, v3, vcc
	v_add_co_u32_e32 v10, vcc, 0x3c01000, v8
	s_nop 1
	v_addc_co_u32_e32 v11, vcc, 0, v9, vcc
	v_add_co_u32_e32 v0, vcc, 0x3c00000, v0
	global_load_dwordx4 v[40:43], v[6:7], off offset:256 nt
	global_load_dwordx4 v[44:47], v[10:11], off offset:256 nt
	v_addc_co_u32_e32 v1, vcc, 0, v1, vcc
	v_add_co_u32_e32 v4, vcc, 0x3c00000, v4
	s_nop 1
	v_addc_co_u32_e32 v5, vcc, 0, v5, vcc
	global_load_dwordx4 v[48:51], v[0:1], off offset:256 nt
	global_load_dwordx4 v[52:55], v[4:5], off offset:256 nt
	v_add_co_u32_e32 v0, vcc, 0x3c00000, v2
	s_nop 1
	v_addc_co_u32_e32 v1, vcc, 0, v3, vcc
	v_add_co_u32_e32 v2, vcc, 0x3c00000, v8
	s_nop 1
	v_addc_co_u32_e32 v3, vcc, 0, v9, vcc
	global_load_dwordx4 v[56:59], v[0:1], off offset:256 nt
	global_load_dwordx4 v[60:63], v[2:3], off offset:256 nt
	s_and_b32 s3, s86, 0x8000
	v_add_u32_e32 v148, s3, v142
	v_add_u32_e32 v149, v143, v148
	ds_read_b64_tr_b16 v[0:1],v149 offset:0
	ds_read_b64_tr_b16 v[2:3],v149 offset:128
	ds_read_b64_tr_b16 v[20:21],v149 offset:512
	ds_read_b64_tr_b16 v[22:23],v149 offset:640
	ds_read_b64_tr_b16 v[24:25],v149 offset:4096
	ds_read_b64_tr_b16 v[26:27],v149 offset:4224
	ds_read_b64_tr_b16 v[28:29],v149 offset:4608
	ds_read_b64_tr_b16 v[30:31],v149 offset:4736
	s_waitcnt lgkmcnt(0)
	s_waitcnt vmcnt(19)
	v_mfma_f32_32x32x16_bf16 v[0:15], v[16:19], v[0:3], 0
	s_waitcnt vmcnt(18)
	v_mfma_f32_32x32x16_bf16 v[0:15], v[150:153], v[20:23], v[0:15]
	ds_read_b64_tr_b16 v[20:21],v149 offset:2048
	ds_read_b64_tr_b16 v[22:23],v149 offset:2176
	ds_read_b64_tr_b16 v[162:163],v149 offset:2560
	ds_read_b64_tr_b16 v[164:165],v149 offset:2688
	ds_read_b64_tr_b16 v[166:167],v149 offset:6144
	ds_read_b64_tr_b16 v[168:169],v149 offset:6272
	ds_read_b64_tr_b16 v[170:171],v149 offset:6656
	s_waitcnt vmcnt(17)
	v_mfma_f32_32x32x16_bf16 v[0:15], v[154:157], v[24:27], v[0:15]
	ds_read_b64_tr_b16 v[172:173],v149 offset:6784
	s_waitcnt lgkmcnt(0)
	s_waitcnt vmcnt(16)
	v_mfma_f32_32x32x16_bf16 v[0:15], v[158:161], v[28:31], v[0:15]
	v_mfma_f32_32x32x16_bf16 v[16:31], v[16:19], v[20:23], 0
	v_mfma_f32_32x32x16_bf16 v[16:31], v[150:153], v[162:165], v[16:31]
	v_mfma_f32_32x32x16_bf16 v[16:31], v[154:157], v[166:169], v[16:31]
	v_mfma_f32_32x32x16_bf16 v[16:31], v[158:161], v[170:173], v[16:31]
	s_and_saveexec_b64 vcc, s[6:7]
	s_cbranch_execz .Lg2_new165
	v_add3_u32 v120, v148, v143, s34
	ds_read_b64_tr_b16 v[166:167],v120 offset:0
	ds_read_b64_tr_b16 v[168:169],v120 offset:128
	ds_read_b64_tr_b16 v[170:171],v120 offset:512
	ds_read_b64_tr_b16 v[172:173],v120 offset:640
	ds_read_b64_tr_b16 v[178:179],v120 offset:4096
	ds_read_b64_tr_b16 v[180:181],v120 offset:4224
	ds_read_b64_tr_b16 v[182:183],v120 offset:4608
	ds_read_b64_tr_b16 v[184:185],v120 offset:4736
	s_waitcnt lgkmcnt(0)
	s_waitcnt vmcnt(15)
	v_mfma_f32_32x32x16_bf16 v[0:15], v[186:189], v[166:169], v[0:15]
	ds_read_b64_tr_b16 v[166:167],v120 offset:2048
	ds_read_b64_tr_b16 v[168:169],v120 offset:2176
	s_waitcnt vmcnt(14)
	v_mfma_f32_32x32x16_bf16 v[0:15], v[190:193], v[170:173], v[0:15]
	ds_read_b64_tr_b16 v[170:171],v120 offset:2560
	ds_read_b64_tr_b16 v[172:173],v120 offset:2688
	s_waitcnt vmcnt(13)
	v_mfma_f32_32x32x16_bf16 v[0:15], v[194:197], v[178:181], v[0:15]
	ds_read_b64_tr_b16 v[178:179],v120 offset:6144
	ds_read_b64_tr_b16 v[180:181],v120 offset:6272
	s_waitcnt vmcnt(12)
	v_mfma_f32_32x32x16_bf16 v[0:15], v[198:201], v[182:185], v[0:15]
	ds_read_b64_tr_b16 v[182:183],v120 offset:6656
	ds_read_b64_tr_b16 v[184:185],v120 offset:6784
	s_waitcnt lgkmcnt(0)
	v_mfma_f32_32x32x16_bf16 v[16:31], v[186:189], v[166:169], v[16:31]
	v_mfma_f32_32x32x16_bf16 v[16:31], v[190:193], v[170:173], v[16:31]
	v_mfma_f32_32x32x16_bf16 v[16:31], v[194:197], v[178:181], v[16:31]
	v_mfma_f32_32x32x16_bf16 v[16:31], v[198:201], v[182:185], v[16:31]
.Lg2_new165:
	s_or_b64 exec, exec, vcc
	s_waitcnt vmcnt(8)
	s_branch .Lg2_cont

.Lg2_cont:
	s_nop 6
	v_add_f32_e32 v0, v92, v0
	v_add_f32_e32 v1, v93, v1
	v_cndmask_b32_e64 v120, v0, v1, s[8:9]
	v_mov_b32_e32 v121, 0
	s_mov_b64 s[36:37], -1
	s_and_b64 vcc, exec, s[22:23]
	v_mov_b32_dpp v121, v120 quad_perm:[1,0,3,2] row_mask:0xf bank_mask:0xf
	v_cndmask_b32_e64 v0, v121, v0, s[8:9]
	v_cndmask_b32_e64 v1, v1, v121, s[8:9]
	v_cvt_pk_bf16_f32 v0, v0, v1
	ds_write_b32 v128, v0
	v_add_f32_e32 v0, v92, v16
	v_add_f32_e32 v1, v93, v17
	v_cndmask_b32_e64 v16, v0, v1, s[8:9]
	v_mov_b32_e32 v17, 0
	s_nop 1
	v_mov_b32_dpp v17, v16 quad_perm:[1,0,3,2] row_mask:0xf bank_mask:0xf
	v_cndmask_b32_e64 v0, v17, v0, s[8:9]
	v_cndmask_b32_e64 v1, v1, v17, s[8:9]
	v_cvt_pk_bf16_f32 v0, v0, v1
	ds_write_b32 v128, v0 offset:64
	v_add_f32_e32 v0, v94, v2
	v_add_f32_e32 v1, v95, v3
	v_cndmask_b32_e64 v2, v0, v1, s[8:9]
	v_mov_b32_e32 v3, 0
	s_nop 1
	v_mov_b32_dpp v3, v2 quad_perm:[1,0,3,2] row_mask:0xf bank_mask:0xf
	v_cndmask_b32_e64 v0, v3, v0, s[8:9]
	v_cndmask_b32_e64 v1, v1, v3, s[8:9]
	v_cvt_pk_bf16_f32 v0, v0, v1
	ds_write_b32 v128, v0 offset:544
	v_add_f32_e32 v0, v94, v18
	v_add_f32_e32 v1, v95, v19
	v_cndmask_b32_e64 v2, v0, v1, s[8:9]
	v_mov_b32_e32 v3, 0
	s_nop 1
	v_mov_b32_dpp v3, v2 quad_perm:[1,0,3,2] row_mask:0xf bank_mask:0xf
	v_cndmask_b32_e64 v0, v3, v0, s[8:9]
	v_cndmask_b32_e64 v1, v1, v3, s[8:9]
	v_cvt_pk_bf16_f32 v0, v0, v1
	ds_write_b32 v128, v0 offset:608
	v_add_f32_e32 v0, v88, v4
	v_add_f32_e32 v1, v89, v5
	v_cndmask_b32_e64 v2, v0, v1, s[8:9]
	v_mov_b32_e32 v3, 0
	v_lshlrev_b32_e32 v4, 16, v76
	s_nop 0
	v_mov_b32_dpp v3, v2 quad_perm:[1,0,3,2] row_mask:0xf bank_mask:0xf
	v_cndmask_b32_e64 v0, v3, v0, s[8:9]
	v_cndmask_b32_e64 v1, v1, v3, s[8:9]
	v_cvt_pk_bf16_f32 v0, v0, v1
	ds_write_b32 v128, v0 offset:2176
	v_add_f32_e32 v0, v88, v20
	v_add_f32_e32 v1, v89, v21
	v_cndmask_b32_e64 v2, v0, v1, s[8:9]
	v_mov_b32_e32 v3, 0
	s_nop 1
	v_mov_b32_dpp v3, v2 quad_perm:[1,0,3,2] row_mask:0xf bank_mask:0xf
	v_cndmask_b32_e64 v0, v3, v0, s[8:9]
	v_cndmask_b32_e64 v1, v1, v3, s[8:9]
	v_cvt_pk_bf16_f32 v0, v0, v1
	ds_write_b32 v128, v0 offset:2240
	v_add_f32_e32 v0, v90, v6
	v_add_f32_e32 v1, v91, v7
	v_cndmask_b32_e64 v2, v0, v1, s[8:9]
	v_mov_b32_e32 v3, 0
	s_nop 1
	v_mov_b32_dpp v3, v2 quad_perm:[1,0,3,2] row_mask:0xf bank_mask:0xf
	v_cndmask_b32_e64 v0, v3, v0, s[8:9]
	v_cndmask_b32_e64 v1, v1, v3, s[8:9]
	v_cvt_pk_bf16_f32 v0, v0, v1
	ds_write_b32 v128, v0 offset:2720
	v_add_f32_e32 v0, v90, v22
	v_add_f32_e32 v1, v91, v23
	v_cndmask_b32_e64 v2, v0, v1, s[8:9]
	v_mov_b32_e32 v3, 0
	s_nop 1
	v_mov_b32_dpp v3, v2 quad_perm:[1,0,3,2] row_mask:0xf bank_mask:0xf
	v_cndmask_b32_e64 v0, v3, v0, s[8:9]
	v_cndmask_b32_e64 v1, v1, v3, s[8:9]
	v_cvt_pk_bf16_f32 v0, v0, v1
	ds_write_b32 v128, v0 offset:2784
	v_add_f32_e32 v0, v84, v8
	v_add_f32_e32 v1, v85, v9
	v_cndmask_b32_e64 v2, v0, v1, s[8:9]
	v_mov_b32_e32 v3, 0
	v_lshl_add_u64 v[8:9], v[106:107], 0, s[46:47]
	s_nop 0
	v_mov_b32_dpp v3, v2 quad_perm:[1,0,3,2] row_mask:0xf bank_mask:0xf
	v_cndmask_b32_e64 v0, v3, v0, s[8:9]
	v_cndmask_b32_e64 v1, v1, v3, s[8:9]
	v_cvt_pk_bf16_f32 v0, v0, v1
	ds_write_b32 v128, v0 offset:4352
	v_add_f32_e32 v0, v84, v24
	v_add_f32_e32 v1, v85, v25
	v_cndmask_b32_e64 v2, v0, v1, s[8:9]
	v_mov_b32_e32 v3, 0
	s_nop 1
	v_mov_b32_dpp v3, v2 quad_perm:[1,0,3,2] row_mask:0xf bank_mask:0xf
	v_cndmask_b32_e64 v0, v3, v0, s[8:9]
	v_cndmask_b32_e64 v1, v1, v3, s[8:9]
	v_cvt_pk_bf16_f32 v0, v0, v1
	ds_write_b32 v128, v0 offset:4416
	v_add_f32_e32 v0, v86, v10
	v_add_f32_e32 v1, v87, v11
	v_cndmask_b32_e64 v2, v0, v1, s[8:9]
	v_mov_b32_e32 v3, 0
	s_nop 1
	v_mov_b32_dpp v3, v2 quad_perm:[1,0,3,2] row_mask:0xf bank_mask:0xf
	v_cndmask_b32_e64 v0, v3, v0, s[8:9]
	v_cndmask_b32_e64 v1, v1, v3, s[8:9]
	v_cvt_pk_bf16_f32 v0, v0, v1
	ds_write_b32 v128, v0 offset:4896
	v_add_f32_e32 v0, v86, v26
	v_add_f32_e32 v1, v87, v27
	v_cndmask_b32_e64 v2, v0, v1, s[8:9]
	v_mov_b32_e32 v3, 0
	s_nop 1
	v_mov_b32_dpp v3, v2 quad_perm:[1,0,3,2] row_mask:0xf bank_mask:0xf
	v_cndmask_b32_e64 v0, v3, v0, s[8:9]
	v_cndmask_b32_e64 v1, v1, v3, s[8:9]
	v_cvt_pk_bf16_f32 v0, v0, v1
	ds_write_b32 v128, v0 offset:4960
	v_add_f32_e32 v0, v80, v12
	v_add_f32_e32 v1, v81, v13
	v_cndmask_b32_e64 v2, v0, v1, s[8:9]
	v_mov_b32_e32 v3, 0
	s_nop 1
	v_mov_b32_dpp v3, v2 quad_perm:[1,0,3,2] row_mask:0xf bank_mask:0xf
	v_cndmask_b32_e64 v0, v3, v0, s[8:9]
	v_cndmask_b32_e64 v1, v1, v3, s[8:9]
	v_cvt_pk_bf16_f32 v0, v0, v1
	ds_write_b32 v128, v0 offset:6528
	v_add_f32_e32 v0, v80, v28
	v_add_f32_e32 v1, v81, v29
	v_cndmask_b32_e64 v2, v0, v1, s[8:9]
	v_mov_b32_e32 v3, 0
	s_nop 1
	v_mov_b32_dpp v3, v2 quad_perm:[1,0,3,2] row_mask:0xf bank_mask:0xf
	v_cndmask_b32_e64 v0, v3, v0, s[8:9]
	v_cndmask_b32_e64 v1, v1, v3, s[8:9]
	v_cvt_pk_bf16_f32 v0, v0, v1
	ds_write_b32 v128, v0 offset:6592
	v_add_f32_e32 v0, v82, v14
	v_add_f32_e32 v1, v83, v15
	v_cndmask_b32_e64 v2, v0, v1, s[8:9]
	v_mov_b32_e32 v3, 0
	s_nop 1
	v_mov_b32_dpp v3, v2 quad_perm:[1,0,3,2] row_mask:0xf bank_mask:0xf
	v_cndmask_b32_e64 v0, v3, v0, s[8:9]
	v_cndmask_b32_e64 v1, v1, v3, s[8:9]
	v_cvt_pk_bf16_f32 v0, v0, v1
	ds_write_b32 v128, v0 offset:7072
	v_add_f32_e32 v0, v82, v30
	v_add_f32_e32 v1, v83, v31
	v_cndmask_b32_e64 v2, v0, v1, s[8:9]
	v_mov_b32_e32 v3, 0
	s_nop 1
	v_mov_b32_dpp v3, v2 quad_perm:[1,0,3,2] row_mask:0xf bank_mask:0xf
	v_cndmask_b32_e64 v0, v3, v0, s[8:9]
	v_cndmask_b32_e64 v1, v1, v3, s[8:9]
	v_cvt_pk_bf16_f32 v0, v0, v1
	ds_write_b32 v128, v0 offset:7136
	s_waitcnt lgkmcnt(0)
	s_barrier
	ds_read_b128 v[0:3], v144
	s_waitcnt lgkmcnt(0)
	v_lshlrev_b32_e32 v5, 16, v0
	v_mul_f32_e32 v4, v5, v4
	v_and_b32_e32 v0, 0xffff0000, v0
	v_and_b32_e32 v5, 0xffff0000, v76
	v_mul_f32_e32 v0, v0, v5
	v_cvt_pk_bf16_f32 v0, v4, v0
	v_lshlrev_b32_e32 v4, 16, v77
	v_lshlrev_b32_e32 v5, 16, v1
	v_mul_f32_e32 v4, v5, v4
	v_and_b32_e32 v1, 0xffff0000, v1
	v_and_b32_e32 v5, 0xffff0000, v77
	v_mul_f32_e32 v1, v1, v5
	v_cvt_pk_bf16_f32 v1, v4, v1
	v_lshlrev_b32_e32 v4, 16, v78
	v_lshlrev_b32_e32 v5, 16, v2
	v_mul_f32_e32 v4, v5, v4
	v_and_b32_e32 v2, 0xffff0000, v2
	v_and_b32_e32 v5, 0xffff0000, v78
	v_mul_f32_e32 v2, v2, v5
	v_cvt_pk_bf16_f32 v2, v4, v2
	v_lshlrev_b32_e32 v4, 16, v79
	v_lshlrev_b32_e32 v5, 16, v3
	v_mul_f32_e32 v4, v5, v4
	v_and_b32_e32 v3, 0xffff0000, v3
	v_and_b32_e32 v5, 0xffff0000, v79
	v_mul_f32_e32 v3, v3, v5
	v_cvt_pk_bf16_f32 v3, v4, v3
	ds_read_b128 v[4:7], v145
	global_store_dwordx4 v[8:9], v[0:3], off
	v_lshl_add_u64 v[8:9], v[108:109], 0, s[46:47]
	s_nop 0
	v_lshlrev_b32_e32 v0, 16, v72
	s_waitcnt lgkmcnt(0)
	v_lshlrev_b32_e32 v1, 16, v4
	v_mul_f32_e32 v0, v1, v0
	v_and_b32_e32 v1, 0xffff0000, v4
	v_and_b32_e32 v2, 0xffff0000, v72
	v_mul_f32_e32 v1, v1, v2
	v_cvt_pk_bf16_f32 v0, v0, v1
	v_lshlrev_b32_e32 v1, 16, v73
	v_lshlrev_b32_e32 v2, 16, v5
	v_mul_f32_e32 v1, v2, v1
	v_and_b32_e32 v2, 0xffff0000, v5
	v_and_b32_e32 v3, 0xffff0000, v73
	v_mul_f32_e32 v2, v2, v3
	v_cvt_pk_bf16_f32 v1, v1, v2
	v_lshlrev_b32_e32 v2, 16, v74
	v_lshlrev_b32_e32 v3, 16, v6
	v_mul_f32_e32 v2, v3, v2
	v_and_b32_e32 v3, 0xffff0000, v6
	v_and_b32_e32 v4, 0xffff0000, v74
	v_mul_f32_e32 v3, v3, v4
	v_cvt_pk_bf16_f32 v2, v2, v3
	v_lshlrev_b32_e32 v3, 16, v75
	v_lshlrev_b32_e32 v4, 16, v7
	v_mul_f32_e32 v3, v4, v3
	v_and_b32_e32 v4, 0xffff0000, v7
	v_and_b32_e32 v5, 0xffff0000, v75
	v_mul_f32_e32 v4, v4, v5
	v_cvt_pk_bf16_f32 v3, v3, v4
	ds_read_b128 v[4:7], v146
	global_store_dwordx4 v[8:9], v[0:3], off
	v_lshl_add_u64 v[8:9], v[110:111], 0, s[46:47]
	s_nop 0
	v_lshlrev_b32_e32 v0, 16, v68
	s_waitcnt lgkmcnt(0)
	v_lshlrev_b32_e32 v1, 16, v4
	v_mul_f32_e32 v0, v1, v0
	v_and_b32_e32 v1, 0xffff0000, v4
	v_and_b32_e32 v2, 0xffff0000, v68
	v_mul_f32_e32 v1, v1, v2
	v_cvt_pk_bf16_f32 v0, v0, v1
	v_lshlrev_b32_e32 v1, 16, v69
	v_lshlrev_b32_e32 v2, 16, v5
	v_mul_f32_e32 v1, v2, v1
	v_and_b32_e32 v2, 0xffff0000, v5
	v_and_b32_e32 v3, 0xffff0000, v69
	v_mul_f32_e32 v2, v2, v3
	v_cvt_pk_bf16_f32 v1, v1, v2
	v_lshlrev_b32_e32 v2, 16, v70
	v_lshlrev_b32_e32 v3, 16, v6
	v_mul_f32_e32 v2, v3, v2
	v_and_b32_e32 v3, 0xffff0000, v6
	v_and_b32_e32 v4, 0xffff0000, v70
	v_mul_f32_e32 v3, v3, v4
	v_cvt_pk_bf16_f32 v2, v2, v3
	v_lshlrev_b32_e32 v3, 16, v71
	v_lshlrev_b32_e32 v4, 16, v7
	v_mul_f32_e32 v3, v4, v3
	v_and_b32_e32 v4, 0xffff0000, v7
	v_and_b32_e32 v5, 0xffff0000, v71
	v_mul_f32_e32 v4, v4, v5
	v_cvt_pk_bf16_f32 v3, v3, v4
	ds_read_b128 v[4:7], v147
	global_store_dwordx4 v[8:9], v[0:3], off
	s_nop 1
	v_lshlrev_b32_e32 v0, 16, v64
	s_waitcnt lgkmcnt(0)
	v_lshlrev_b32_e32 v1, 16, v4
	v_mul_f32_e32 v0, v1, v0
	v_and_b32_e32 v1, 0xffff0000, v4
	v_and_b32_e32 v2, 0xffff0000, v64
	v_mul_f32_e32 v1, v1, v2
	v_cvt_pk_bf16_f32 v0, v0, v1
	v_lshlrev_b32_e32 v1, 16, v65
	v_lshlrev_b32_e32 v2, 16, v5
	v_mul_f32_e32 v1, v2, v1
	v_and_b32_e32 v2, 0xffff0000, v5
	v_and_b32_e32 v3, 0xffff0000, v65
	v_mul_f32_e32 v2, v2, v3
	v_cvt_pk_bf16_f32 v1, v1, v2
	v_lshlrev_b32_e32 v2, 16, v66
	v_lshlrev_b32_e32 v3, 16, v6
	v_mul_f32_e32 v2, v3, v2
	v_and_b32_e32 v3, 0xffff0000, v6
	v_and_b32_e32 v4, 0xffff0000, v66
	v_mul_f32_e32 v3, v3, v4
	v_cvt_pk_bf16_f32 v2, v2, v3
	v_lshlrev_b32_e32 v3, 16, v67
	v_lshlrev_b32_e32 v4, 16, v7
	v_mul_f32_e32 v3, v4, v3
	v_and_b32_e32 v4, 0xffff0000, v7
	v_and_b32_e32 v5, 0xffff0000, v67
	v_mul_f32_e32 v4, v4, v5
	v_cvt_pk_bf16_f32 v3, v3, v4
	v_lshl_add_u64 v[4:5], v[112:113], 0, s[46:47]
	global_store_dwordx4 v[4:5], v[0:3], off
	s_cbranch_vccz .LBB0_167
	v_lshl_add_u64 v[4:5], v[116:117], 0, s[68:69]
	v_lshl_add_u64 v[12:13], v[114:115], 0, s[68:69]
	global_load_dwordx4 v[0:3], v[4:5], off offset:528
	global_load_dwordx4 v[8:11], v[4:5], off offset:512
	s_nop 0
	global_load_dwordx4 v[4:7], v[12:13], off offset:528
	s_nop 0
	global_load_dwordx4 v[12:15], v[12:13], off offset:512
	ds_read_b32 v19, v122
	ds_read_b32 v20, v123
	v_lshlrev_b32_e32 v16, 16, v32
	v_and_b32_e32 v17, 0xffff0000, v32
	v_and_b32_e32 v18, 0xffff0000, v33
	s_waitcnt lgkmcnt(1)
	v_sub_f32_e32 v16, v16, v19
	v_sub_f32_e32 v17, v17, v19
	s_waitcnt lgkmcnt(0)
	v_mul_f32_e32 v16, v20, v16
	v_mul_f32_e32 v17, v20, v17
	v_sub_f32_e32 v18, v18, v19
	v_mul_f32_e32 v18, v20, v18
	v_and_b32_e32 v21, 0xffff0000, v34
	v_sub_f32_e32 v21, v21, v19
	v_mul_f32_e32 v21, v20, v21
	v_and_b32_e32 v22, 0xffff0000, v35
	s_add_u32 s22, s86, 0x8000
	s_addc_u32 s23, s87, 0
	s_and_b32 s3, s22, 0x8000
	s_mov_b64 s[36:37], 0
	s_waitcnt vmcnt(1)
	v_fma_f32 v21, v1, v21, v5
	s_waitcnt vmcnt(0)
	v_fma_f32 v16, v8, v16, v12
	v_fma_f32 v17, v9, v17, v13
	v_cvt_pk_bf16_f32 v16, v16, v17
	v_lshlrev_b32_e32 v17, 16, v33
	v_sub_f32_e32 v17, v17, v19
	v_mul_f32_e32 v17, v20, v17
	v_fma_f32 v17, v10, v17, v14
	v_fma_f32 v18, v11, v18, v15
	v_cvt_pk_bf16_f32 v17, v17, v18
	v_lshlrev_b32_e32 v18, 16, v34
	v_sub_f32_e32 v18, v18, v19
	v_mul_f32_e32 v18, v20, v18
	v_fma_f32 v18, v0, v18, v4
	v_cvt_pk_bf16_f32 v18, v18, v21
	v_lshlrev_b32_e32 v21, 16, v35
	v_sub_f32_e32 v21, v21, v19
	v_sub_f32_e32 v19, v22, v19
	v_mul_f32_e32 v19, v20, v19
	v_mul_f32_e32 v21, v20, v21
	v_fma_f32 v19, v3, v19, v7
	v_add3_u32 v20, s3, v124, v125
	v_fma_f32 v21, v2, v21, v6
	v_cvt_pk_bf16_f32 v19, v21, v19
	ds_write_b128 v20, v[16:19]
	ds_read_b32 v19, v126
	ds_read_b32 v20, v127
	v_lshlrev_b32_e32 v16, 16, v36
	v_and_b32_e32 v17, 0xffff0000, v36
	v_and_b32_e32 v18, 0xffff0000, v37
	s_waitcnt lgkmcnt(1)
	v_sub_f32_e32 v16, v16, v19
	v_sub_f32_e32 v17, v17, v19
	s_waitcnt lgkmcnt(0)
	v_mul_f32_e32 v16, v20, v16
	v_mul_f32_e32 v17, v20, v17
	v_fma_f32 v16, v8, v16, v12
	v_fma_f32 v17, v9, v17, v13
	v_cvt_pk_bf16_f32 v16, v16, v17
	v_lshlrev_b32_e32 v17, 16, v37
	v_sub_f32_e32 v17, v17, v19
	v_sub_f32_e32 v18, v18, v19
	v_mul_f32_e32 v17, v20, v17
	v_mul_f32_e32 v18, v20, v18
	v_fma_f32 v17, v10, v17, v14
	v_fma_f32 v18, v11, v18, v15
	v_cvt_pk_bf16_f32 v17, v17, v18
	v_lshlrev_b32_e32 v18, 16, v38
	v_and_b32_e32 v21, 0xffff0000, v38
	v_sub_f32_e32 v18, v18, v19
	v_sub_f32_e32 v21, v21, v19
	v_mul_f32_e32 v18, v20, v18
	v_mul_f32_e32 v21, v20, v21
	v_fma_f32 v18, v0, v18, v4
	v_fma_f32 v21, v1, v21, v5
	v_cvt_pk_bf16_f32 v18, v18, v21
	v_lshlrev_b32_e32 v21, 16, v39
	v_and_b32_e32 v22, 0xffff0000, v39
	v_sub_f32_e32 v21, v21, v19
	v_sub_f32_e32 v19, v22, v19
	v_mul_f32_e32 v19, v20, v19
	v_mul_f32_e32 v21, v20, v21
	v_fma_f32 v19, v3, v19, v7
	v_add3_u32 v20, s3, v132, v133
	v_fma_f32 v21, v2, v21, v6
	v_cvt_pk_bf16_f32 v19, v21, v19
	ds_write_b128 v20, v[16:19]
	ds_read_b32 v19, v134
	ds_read_b32 v20, v135
	v_lshlrev_b32_e32 v16, 16, v40
	v_and_b32_e32 v17, 0xffff0000, v40
	v_and_b32_e32 v18, 0xffff0000, v41
	s_waitcnt lgkmcnt(1)
	v_sub_f32_e32 v16, v16, v19
	v_sub_f32_e32 v17, v17, v19
	s_waitcnt lgkmcnt(0)
	v_mul_f32_e32 v16, v20, v16
	v_mul_f32_e32 v17, v20, v17
	v_fma_f32 v16, v8, v16, v12
	v_fma_f32 v17, v9, v17, v13
	v_cvt_pk_bf16_f32 v16, v16, v17
	v_lshlrev_b32_e32 v17, 16, v41
	v_sub_f32_e32 v17, v17, v19
	v_sub_f32_e32 v18, v18, v19
	v_mul_f32_e32 v17, v20, v17
	v_mul_f32_e32 v18, v20, v18
	v_fma_f32 v17, v10, v17, v14
	v_fma_f32 v18, v11, v18, v15
	v_cvt_pk_bf16_f32 v17, v17, v18
	v_lshlrev_b32_e32 v18, 16, v42
	v_and_b32_e32 v21, 0xffff0000, v42
	v_sub_f32_e32 v18, v18, v19
	v_sub_f32_e32 v21, v21, v19
	v_mul_f32_e32 v18, v20, v18
	v_mul_f32_e32 v21, v20, v21
	v_fma_f32 v18, v0, v18, v4
	v_fma_f32 v21, v1, v21, v5
	v_cvt_pk_bf16_f32 v18, v18, v21
	v_lshlrev_b32_e32 v21, 16, v43
	v_and_b32_e32 v22, 0xffff0000, v43
	v_sub_f32_e32 v21, v21, v19
	v_sub_f32_e32 v19, v22, v19
	v_mul_f32_e32 v19, v20, v19
	v_mul_f32_e32 v21, v20, v21
	v_fma_f32 v19, v3, v19, v7
	v_add3_u32 v20, s3, v136, v137
	v_fma_f32 v21, v2, v21, v6
	v_cvt_pk_bf16_f32 v19, v21, v19
	ds_write_b128 v20, v[16:19]
	ds_read_b32 v16, v138
	ds_read_b32 v17, v139
	v_lshlrev_b32_e32 v18, 16, v44
	s_waitcnt lgkmcnt(1)
	v_sub_f32_e32 v18, v18, v16
	s_waitcnt lgkmcnt(0)
	v_mul_f32_e32 v18, v17, v18
	v_fma_f32 v8, v8, v18, v12
	v_and_b32_e32 v12, 0xffff0000, v44
	v_sub_f32_e32 v12, v12, v16
	v_mul_f32_e32 v12, v17, v12
	v_fma_f32 v9, v9, v12, v13
	v_cvt_pk_bf16_f32 v8, v8, v9
	v_lshlrev_b32_e32 v9, 16, v45
	v_sub_f32_e32 v9, v9, v16
	v_mul_f32_e32 v9, v17, v9
	v_fma_f32 v9, v10, v9, v14
	v_and_b32_e32 v10, 0xffff0000, v45
	v_sub_f32_e32 v10, v10, v16
	v_mul_f32_e32 v10, v17, v10
	v_fmac_f32_e32 v15, v11, v10
	v_lshlrev_b32_e32 v10, 16, v46
	v_sub_f32_e32 v10, v10, v16
	v_mul_f32_e32 v10, v17, v10
	v_fma_f32 v0, v0, v10, v4
	v_and_b32_e32 v4, 0xffff0000, v46
	v_sub_f32_e32 v4, v4, v16
	v_mul_f32_e32 v4, v17, v4
	v_cvt_pk_bf16_f32 v9, v9, v15
	v_fma_f32 v1, v1, v4, v5
	v_cvt_pk_bf16_f32 v10, v0, v1
	v_lshlrev_b32_e32 v0, 16, v47
	v_sub_f32_e32 v0, v0, v16
	v_and_b32_e32 v1, 0xffff0000, v47
	v_mul_f32_e32 v0, v17, v0
	v_sub_f32_e32 v1, v1, v16
	v_fma_f32 v0, v2, v0, v6
	v_mul_f32_e32 v1, v17, v1
	v_fmac_f32_e32 v7, v3, v1
	v_cvt_pk_bf16_f32 v11, v0, v7
	v_add3_u32 v0, s3, v140, v141
	ds_write_b128 v0, v[8:11]
